# v64 + attention step loops: K ring slot offset computed once per iteration into s32 and reused by the second-half K DMA (2 SALU fewer per iteration)
# baseline (speedup 1.0000x reference)
.LBB0_789:
	s_mul_hi_u32 s4, s61, 0xaaaaaaab
	s_lshr_b32 s50, s4, 1
	s_mul_i32 s32, s50, 0xffffa000
	s_add_i32 s32, s14, s32
	s_and_b32 s51, s14, 0x6000
	v_add_u32_e32 v217, s32, v214
	v_add_u32_e32 v216, s51, v147
	v_add_u32_e32 v217, 0xffffc000, v217
	ds_read_b64_tr_b16 v[118:119], v216 offset:24576
	ds_read_b64_tr_b16 v[120:121], v216 offset:25088
	ds_read_b64_tr_b16 v[122:123], v216 offset:28672
	ds_read_b64_tr_b16 v[124:125], v216 offset:29184
	ds_read_b128 v[114:117], v217
	s_waitcnt lgkmcnt(3)
	v_mfma_f32_32x32x16_bf16 v[18:33], v[164:167], v[118:121], v[18:33]
	ds_read_b64_tr_b16 v[126:127], v216 offset:57344
	ds_read_b64_tr_b16 v[128:129], v216 offset:57856
	s_waitcnt lgkmcnt(3)
	v_mfma_f32_32x32x16_bf16 v[50:65], v[164:167], v[122:125], v[50:65]
	ds_read_b64_tr_b16 v[130:131], v216 offset:61440
	ds_read_b64_tr_b16 v[132:133], v216 offset:61952
	s_waitcnt lgkmcnt(2)
	v_mfma_f32_32x32x16_bf16 v[34:49], v[164:167], v[126:129], v[34:49]
	ds_read_b64_tr_b16 v[118:119], v216 offset:25600
	ds_read_b64_tr_b16 v[120:121], v216 offset:26112
	s_waitcnt lgkmcnt(2)
	v_mfma_f32_32x32x16_bf16 v[2:17], v[164:167], v[130:133], v[2:17]
	ds_read_b64_tr_b16 v[180:181], v216 offset:29696
	ds_read_b64_tr_b16 v[182:183], v216 offset:30208
	v_max_f32_e32 v122, v98, v99
	v_max3_f32 v123, v100, v101, v67
	v_max3_f32 v122, v122, v66, v68
	v_max3_f32 v122, v122, v69, v102
	v_max3_f32 v123, v123, v104, v105
	v_max3_f32 v122, v122, v103, v70
	v_max3_f32 v123, v123, v72, v73
	v_max3_f32 v122, v122, v71, v106
	v_max3_f32 v123, v123, v108, v109
	v_max3_f32 v122, v122, v107, v74
	v_max3_f32 v123, v123, v76, v77
	v_max3_f32 v122, v122, v75, v110
	v_max3_f32 v123, v123, v112, v113
	v_max3_f32 v122, v122, v111, v78
	v_max3_f32 v123, v123, v80, v81
	v_max3_f32 v122, v122, v79, v123
	v_mov_b32_e32 v123, v122
	s_nop 1
	v_permlane32_swap_b32_e32 v122, v123
	v_max_f32_e32 v122, v122, v123
	v_cmp_lt_f32_e32 vcc, s15, v122
	s_mov_b64 s[4:5], vcc
	s_cbranch_vccnz .Lattn_rare_m0_a1

.LBB0_797:
	s_andn2_b64 vcc, exec, s[94:95]
	s_cbranch_vccnz .LBB0_812
	s_waitcnt vmcnt(3) lgkmcnt(0)
	s_barrier
	s_add_i32 s29, s30, 2
	s_cmp_ge_i32 s29, s71
	s_cbranch_scc1 .LBB0_800
	s_add_i32 s4, s56, s32
	s_addk_i32 s4, 0xc000
	s_mov_b32 m0, s4
	v_lshl_add_u64 v[68:69], v[192:193], 0, s[44:45]
	global_load_lds_dwordx4 v[68:69], off
	s_andn2_b64 vcc, exec, s[94:95]
	s_cbranch_vccnz .LBB0_802

.LBB0_818:
	s_add_i32 s4, s56, s32
	s_addk_i32 s4, 0xc000
	s_mov_b32 m0, s4
	v_lshl_add_u64 v[68:69], v[192:193], 0, s[44:45]
	global_load_lds_dwordx4 v[68:69], off
	s_andn2_b64 vcc, exec, s[94:95]
	s_cbranch_vccz .LBB0_801
	s_branch .LBB0_802

.LBB0_857:
	s_mul_hi_u32 s4, s56, 0xaaaaaaab
	s_lshr_b32 s50, s4, 1
	s_mul_i32 s32, s50, 0xffffa000
	s_add_i32 s32, s14, s32
	s_and_b32 s51, s14, 0x6000
	v_add_u32_e32 v216, s32, v187
	v_add_u32_e32 v215, s51, v209
	v_add_u32_e32 v216, 0xffffc000, v216
	ds_read_b64_tr_b16 v[118:119], v215 offset:24576
	ds_read_b64_tr_b16 v[120:121], v215 offset:25088
	ds_read_b64_tr_b16 v[122:123], v215 offset:28672
	ds_read_b64_tr_b16 v[124:125], v215 offset:29184
	ds_read_b128 v[114:117], v216
	s_waitcnt lgkmcnt(3)
	v_mfma_f32_32x32x16_bf16 v[18:33], v[164:167], v[118:121], v[18:33]
	ds_read_b64_tr_b16 v[126:127], v215 offset:57344
	ds_read_b64_tr_b16 v[128:129], v215 offset:57856
	s_waitcnt lgkmcnt(3)
	v_mfma_f32_32x32x16_bf16 v[50:65], v[164:167], v[122:125], v[50:65]
	ds_read_b64_tr_b16 v[130:131], v215 offset:61440
	ds_read_b64_tr_b16 v[132:133], v215 offset:61952
	s_waitcnt lgkmcnt(2)
	v_mfma_f32_32x32x16_bf16 v[34:49], v[164:167], v[126:129], v[34:49]
	ds_read_b64_tr_b16 v[118:119], v215 offset:25600
	ds_read_b64_tr_b16 v[120:121], v215 offset:26112
	s_waitcnt lgkmcnt(2)
	v_mfma_f32_32x32x16_bf16 v[2:17], v[164:167], v[130:133], v[2:17]
	ds_read_b64_tr_b16 v[180:181], v215 offset:29696
	ds_read_b64_tr_b16 v[182:183], v215 offset:30208
	v_max_f32_e32 v122, v98, v99
	v_max3_f32 v123, v100, v101, v67
	v_max3_f32 v122, v122, v66, v68
	v_max3_f32 v122, v122, v69, v102
	v_max3_f32 v123, v123, v104, v105
	v_max3_f32 v122, v122, v103, v70
	v_max3_f32 v123, v123, v72, v73
	v_max3_f32 v122, v122, v71, v106
	v_max3_f32 v123, v123, v108, v109
	v_max3_f32 v122, v122, v107, v74
	v_max3_f32 v123, v123, v76, v77
	v_max3_f32 v122, v122, v75, v110
	v_max3_f32 v123, v123, v112, v113
	v_max3_f32 v122, v122, v111, v78
	v_max3_f32 v123, v123, v80, v81
	v_max3_f32 v122, v122, v79, v123
	v_mov_b32_e32 v123, v122
	s_nop 1
	v_permlane32_swap_b32_e32 v122, v123
	v_max_f32_e32 v122, v122, v123
	v_cmp_lt_f32_e32 vcc, s15, v122
	s_mov_b64 s[4:5], vcc
	s_cbranch_vccnz .Lattn_rare_m1_a1

.LBB0_865:
	s_andn2_b64 vcc, exec, s[76:77]
	s_cbranch_vccnz .LBB0_880
	s_waitcnt vmcnt(3) lgkmcnt(0)
	s_barrier
	s_add_i32 s29, s30, 2
	s_cmp_ge_i32 s29, s71
	s_cbranch_scc1 .LBB0_868
	s_add_i32 s4, s25, s32
	s_addk_i32 s4, 0xc000
	s_mov_b32 m0, s4
	v_lshl_add_u64 v[68:69], v[192:193], 0, s[44:45]
	global_load_lds_dwordx4 v[68:69], off
	s_andn2_b64 vcc, exec, s[76:77]
	s_cbranch_vccnz .LBB0_870

.LBB0_886:
	s_add_i32 s4, s25, s32
	s_addk_i32 s4, 0xc000
	s_mov_b32 m0, s4
	v_lshl_add_u64 v[68:69], v[192:193], 0, s[44:45]
	global_load_lds_dwordx4 v[68:69], off
	s_andn2_b64 vcc, exec, s[76:77]
	s_cbranch_vccz .LBB0_869
	s_branch .LBB0_870
